# P4 queue: scan units claimed first (dep satisfied early), then fox-long
# speedup vs baseline: 1.0172x; 1.0002x over previous
; DI void norm_unit(const Params& p, int layer, int half, int nu, int tid) { norm_rows(p, layer, half * HROWS + nu * 64, 64, 0, 8, tid); }
; #define otid() otid_(wbase)
; __global__ void __launch_bounds__(NTHR) mega(Params p) {
;     ...
;         for (;;) {
;           __syncthreads();
;           if (otid() == 0) s_unit = atomicAdd(my, 1);
;           __syncthreads();
;           const int u0 = s_unit;
;           const int n_fill = (hf == 1) ? 256 : 0;
;           int u = u0;
;           if (u >= 1344 + n_fill) break;
;           if (u >= 448 && u < 448 + n_fill) { norm_unit(p, layer + 1, 0, u - 448, otid()); continue; }
;           if (u >= 448) u -= n_fill;
;           const bool needs = (u >= 448 && u < 576) || (u >= 832);
.LBB0_417:
	s_or_b64 exec, exec, s[0:1]
	s_waitcnt lgkmcnt(0)
	s_barrier
	ds_read_b32 v0, v161 offset:16
	v_readlane_b32 s0, v254, 47
	s_waitcnt lgkmcnt(0)
	v_readfirstlane_b32 s23, v0
	v_cmp_le_i32_e64 s[0:1], s0, v0
	s_and_b64 vcc, exec, s[0:1]
	s_cbranch_vccnz .LBB0_412
	v_writelane_b32 v254, s0, 57
	s_cmpk_gt_i32 s23, 0x1bf
	s_nop 0
	v_writelane_b32 v254, s1, 58
	s_cselect_b64 s[0:1], -1, 0
	v_readlane_b32 s2, v254, 48
	s_cmp_lt_i32 s23, s2
	s_cselect_b64 s[4:5], -1, 0
	s_and_b64 s[4:5], s[0:1], s[4:5]
	s_andn2_b64 vcc, exec, s[4:5]
	s_mov_b64 s[4:5], -1
	s_cbranch_vccz .LBB0_622
	s_and_b64 s[0:1], s[0:1], exec
	v_readlane_b32 s0, v254, 25
	s_cselect_b32 s0, s0, 0
	s_nop 0
	v_writelane_b32 v254, s0, 59
	s_mov_b32 s100, 0xffffff40
	s_cmp_lt_u32 s23, 0xc0
	s_cselect_b32 s100, 0x100, s100
	s_cmp_lt_u32 s23, 0x1c0
	s_cselect_b32 s100, s100, 0
	s_add_i32 s23, s23, s100
	s_sub_i32 s0, s23, s0
	s_add_i32 s16, s0, 0xfffffe40
	v_writelane_b32 v254, s0, 60
	s_cmpk_lt_i32 s0, 0x340
	v_readlane_b32 s4, v254, 53
	s_cselect_b64 s[0:1], -1, 0
	v_readlane_b32 s5, v254, 54
	s_or_b64 s[0:1], s[0:1], s[4:5]
	s_cmpk_lt_u32 s16, 0x80
	v_cndmask_b32_e64 v0, 0, 1, s[0:1]
	v_cndmask_b32_e64 v1, 0, 1, s[4:5]
	s_cselect_b64 vcc, -1, 0
	v_cndmask_b32_e32 v0, v0, v1, vcc
	v_and_b32_e32 v0, 1, v0
	v_cmp_eq_u32_e32 vcc, 1, v0
	s_cbranch_vccnz .LBB0_431
	v_mov_b32_e32 v0, v163
	s_nop 0
	v_cmp_eq_u32_e32 vcc, 0, v0
	s_and_saveexec_b64 s[0:1], vcc
	s_cbranch_execz .LBB0_430
	s_mov_b32 s2, 0x400001
	s_branch .LBB0_423
